# P0 RMSNorm rows: the 7 per-chunk gain-vector loads issued with the row loads, no vmcnt(0) between the bf16 stores
# speedup vs baseline: 1.0510x; 1.0013x over previous
.LBB0_339:
	s_cmpk_gt_i32 s4, 0x3fff
	s_mov_b64 s[0:1], -1
	s_cbranch_scc0 .LBB0_341
	s_add_i32 s12, s4, 0xffffc000
	s_lshl_b64 s[0:1], s[12:13], 13
	v_lshl_add_u64 v[2:3], v[34:35], 0, s[0:1]
	global_load_dwordx4 v[30:33], v[2:3], off
	global_load_dwordx4 v[26:29], v[2:3], off offset:1024
	global_load_dwordx4 v[22:25], v[2:3], off offset:2048
	global_load_dwordx4 v[18:21], v[2:3], off offset:3072
	v_add_co_u32_e32 v62, vcc, s2, v2
	s_lshl_b64 s[14:15], s[12:13], 12
	s_nop 0
	v_addc_co_u32_e32 v63, vcc, 0, v3, vcc
	global_load_dwordx4 v[14:17], v[62:63], off
	global_load_dwordx4 v[10:13], v[62:63], off offset:1024
	global_load_dwordx4 v[2:5], v[62:63], off offset:3072
	global_load_dwordx4 v[6:9], v[62:63], off offset:2048
	global_load_dwordx4 v[74:77], v[38:39], off
	global_load_dwordx4 v[132:135], v[38:39], off offset:1024
	global_load_dwordx4 v[136:139], v[38:39], off offset:2048
	global_load_dwordx4 v[140:143], v[38:39], off offset:3072
	global_load_dwordx4 v[144:147], v[40:41], off
	global_load_dwordx4 v[148:151], v[42:43], off
	global_load_dwordx4 v[152:155], v[44:45], off
	global_load_dwordx4 v[156:159], v[46:47], off
	v_cmp_lt_i32_e32 vcc, v67, v66
	s_waitcnt vmcnt(0)
	v_mov_b32_e32 v78, v31
	v_cndmask_b32_e32 v62, v65, v67, vcc
	v_mov_b32_e32 v79, v27
	v_mov_b32_e32 v84, v33
	v_mov_b32_e32 v85, v29
	v_lshlrev_b32_e32 v73, 2, v62
	v_mov_b32_e32 v62, v30
	v_mov_b32_e32 v63, v26
	v_mov_b32_e32 v80, v32
	v_mov_b32_e32 v81, v28
	v_pk_mul_f32 v[86:87], v[24:25], v[24:25]
	v_pk_mul_f32 v[88:89], v[22:23], v[22:23]
	v_pk_mul_f32 v[78:79], v[78:79], v[78:79]
	v_pk_mul_f32 v[84:85], v[84:85], v[84:85]
	v_pk_mov_b32 v[92:93], v[88:89], v[86:87] op_sel:[1,0]
	v_mov_b32_e32 v89, v87
	v_pk_fma_f32 v[62:63], v[62:63], v[62:63], v[78:79]
	v_pk_fma_f32 v[78:79], v[80:81], v[80:81], v[84:85]
	v_mul_f32_e32 v82, v19, v19
	v_mul_f32_e32 v90, v21, v21
	v_pk_add_f32 v[80:81], v[92:93], v[88:89]
	v_pk_add_f32 v[62:63], v[62:63], v[78:79]
	v_mul_f32_e32 v99, v14, v14
	v_mul_f32_e32 v100, v15, v15
	v_mul_f32_e32 v101, v16, v16
	v_mul_f32_e32 v102, v17, v17
	v_pk_fma_f32 v[86:87], v[18:19], v[18:19], v[82:83] op_sel_hi:[1,1,0]
	v_pk_fma_f32 v[90:91], v[20:21], v[20:21], v[90:91] op_sel_hi:[1,1,0]
	v_pk_add_f32 v[78:79], v[80:81], v[80:81] op_sel:[0,1] op_sel_hi:[1,0]
	v_pk_add_f32 v[62:63], v[62:63], v[62:63] op_sel:[0,1] op_sel_hi:[1,0]
	v_pk_mul_f32 v[94:95], v[12:13], v[12:13]
	v_pk_mul_f32 v[96:97], v[10:11], v[10:11]
	v_mov_b32_e32 v87, v101
	v_mov_b32_e32 v91, v102
	v_mov_b32_e32 v79, v100
	v_mov_b32_e32 v63, v99
	v_pk_mov_b32 v[84:85], v[96:97], v[94:95] op_sel:[1,0]
	v_mov_b32_e32 v97, v95
	v_pk_add_f32 v[80:81], v[86:87], v[90:91]
	v_pk_add_f32 v[62:63], v[62:63], v[78:79]
	v_mul_f32_e32 v82, v7, v7
	v_mul_f32_e32 v98, v9, v9
	v_pk_add_f32 v[84:85], v[84:85], v[96:97]
	v_pk_add_f32 v[62:63], v[62:63], v[80:81]
	v_mul_f32_e32 v103, v2, v2
	v_mul_f32_e32 v104, v3, v3
	v_mul_f32_e32 v105, v4, v4
	v_mul_f32_e32 v106, v5, v5
	v_pk_fma_f32 v[88:89], v[6:7], v[6:7], v[82:83] op_sel_hi:[1,1,0]
	v_pk_fma_f32 v[92:93], v[8:9], v[8:9], v[98:99] op_sel_hi:[1,1,0]
	v_pk_add_f32 v[84:85], v[84:85], v[84:85] op_sel:[0,1] op_sel_hi:[1,0]
	v_pk_add_f32 v[62:63], v[62:63], v[62:63] op_sel:[0,1] op_sel_hi:[1,0]
	v_mov_b32_e32 v89, v105
	v_mov_b32_e32 v93, v106
	v_mov_b32_e32 v85, v104
	v_mov_b32_e32 v63, v103
	v_pk_add_f32 v[86:87], v[88:89], v[92:93]
	v_pk_add_f32 v[62:63], v[62:63], v[84:85]
	v_cmp_lt_i32_e32 vcc, v68, v66
	v_pk_add_f32 v[62:63], v[62:63], v[86:87]
	s_nop 0
	v_add_f32_e32 v62, v62, v63
	ds_bpermute_b32 v63, v73, v62
	v_cndmask_b32_e32 v73, v65, v68, vcc
	v_lshlrev_b32_e32 v73, 2, v73
	v_cmp_lt_i32_e32 vcc, v69, v66
	s_waitcnt lgkmcnt(0)
	v_add_f32_e32 v62, v62, v63
	ds_bpermute_b32 v63, v73, v62
	v_cndmask_b32_e32 v73, v65, v69, vcc
	v_lshlrev_b32_e32 v73, 2, v73
	v_cmp_lt_i32_e32 vcc, v70, v66
	s_waitcnt lgkmcnt(0)
	v_add_f32_e32 v62, v62, v63
	ds_bpermute_b32 v63, v73, v62
	v_cndmask_b32_e32 v73, v65, v70, vcc
	v_lshlrev_b32_e32 v73, 2, v73
	v_cmp_lt_i32_e32 vcc, v71, v66
	s_waitcnt lgkmcnt(0)
	v_add_f32_e32 v62, v62, v63
	ds_bpermute_b32 v63, v73, v62
	v_cndmask_b32_e32 v73, v65, v71, vcc
	v_lshlrev_b32_e32 v73, 2, v73
	v_cmp_lt_i32_e32 vcc, v72, v66
	s_waitcnt lgkmcnt(0)
	v_add_f32_e32 v62, v62, v63
	ds_bpermute_b32 v63, v73, v62
	v_cndmask_b32_e32 v73, v65, v72, vcc
	v_lshlrev_b32_e32 v73, 2, v73
	s_waitcnt lgkmcnt(0)
	v_add_f32_e32 v62, v62, v63
	ds_bpermute_b32 v63, v73, v62
	s_waitcnt lgkmcnt(0)
	v_add_f32_e32 v62, v62, v63
	v_fmamk_f32 v62, v62, 0x3a000000, v1
	v_mul_f32_e32 v63, 0x4f800000, v62
	v_cmp_gt_f32_e32 vcc, s3, v62
	s_nop 1
	v_cndmask_b32_e32 v62, v62, v63, vcc
	v_sqrt_f32_e32 v63, v62
	s_nop 0
	v_add_u32_e32 v73, -1, v63
	v_add_u32_e32 v78, 1, v63
	v_fma_f32 v79, -v73, v63, v62
	v_fma_f32 v80, -v78, v63, v62
	v_cmp_ge_f32_e64 s[0:1], 0, v79
	s_nop 1
	v_cndmask_b32_e64 v63, v63, v73, s[0:1]
	v_cmp_lt_f32_e64 s[0:1], 0, v80
	s_nop 1
	v_cndmask_b32_e64 v63, v63, v78, s[0:1]
	v_mul_f32_e32 v73, 0x37800000, v63
	v_cndmask_b32_e32 v63, v63, v73, vcc
	v_cmp_class_f32_e32 vcc, v62, v64
	s_nop 1
	v_cndmask_b32_e32 v73, v63, v62, vcc
	v_div_scale_f32 v78, s[0:1], v73, v73, 1.0
	v_rcp_f32_e32 v79, v78
	v_div_scale_f32 v80, vcc, 1.0, v73, 1.0
	v_lshl_add_u64 v[62:63], v[36:37], 0, s[14:15]
	v_fma_f32 v81, -v78, v79, 1.0
	v_fmac_f32_e32 v79, v81, v79
	v_mul_f32_e32 v81, v80, v79
	v_fma_f32 v82, -v78, v81, v80
	v_fmac_f32_e32 v81, v82, v79
	v_fma_f32 v78, -v78, v81, v80
	v_div_fmas_f32 v78, v78, v79, v81
	v_div_fixup_f32 v78, v78, v73, 1.0
	v_pk_mul_f32 v[30:31], v[30:31], v[78:79] op_sel_hi:[1,0]
	v_pk_mul_f32 v[32:33], v[32:33], v[78:79] op_sel_hi:[1,0]
	v_pk_mul_f32 v[30:31], v[74:75], v[30:31]
	v_pk_mul_f32 v[32:33], v[76:77], v[32:33]
	v_bfe_u32 v73, v30, 16, 1
	v_bfe_u32 v75, v32, 16, 1
	v_bfe_u32 v74, v31, 16, 1
	v_bfe_u32 v76, v33, 16, 1
	v_add3_u32 v30, v30, v73, s5
	v_add3_u32 v32, v32, v75, s5
	v_add3_u32 v31, v31, v74, s5
	v_add3_u32 v33, v33, v76, s5
	v_lshrrev_b32_e32 v30, 16, v30
	v_lshrrev_b32_e32 v32, 16, v32
	v_and_or_b32 v30, v31, s7, v30
	v_and_or_b32 v31, v33, s7, v32
	global_store_dwordx2 v[62:63], v[30:31], off
	s_nop 1
	v_mov_b32_e32 v30, v132
	v_mov_b32_e32 v31, v133
	v_mov_b32_e32 v32, v134
	v_mov_b32_e32 v33, v135
	v_pk_mul_f32 v[26:27], v[26:27], v[78:79] op_sel_hi:[1,0]
	v_pk_mul_f32 v[28:29], v[28:29], v[78:79] op_sel_hi:[1,0]
	v_pk_mul_f32 v[22:23], v[22:23], v[78:79] op_sel_hi:[1,0]
	v_pk_mul_f32 v[24:25], v[24:25], v[78:79] op_sel_hi:[1,0]
	v_pk_mul_f32 v[18:19], v[18:19], v[78:79] op_sel_hi:[1,0]
	v_pk_mul_f32 v[20:21], v[20:21], v[78:79] op_sel_hi:[1,0]
	v_pk_mul_f32 v[14:15], v[14:15], v[78:79] op_sel_hi:[1,0]
	v_pk_mul_f32 v[16:17], v[16:17], v[78:79] op_sel_hi:[1,0]
	v_pk_mul_f32 v[10:11], v[10:11], v[78:79] op_sel_hi:[1,0]
	v_pk_mul_f32 v[12:13], v[12:13], v[78:79] op_sel_hi:[1,0]
	v_pk_mul_f32 v[6:7], v[6:7], v[78:79] op_sel_hi:[1,0]
	v_pk_mul_f32 v[8:9], v[8:9], v[78:79] op_sel_hi:[1,0]
	v_pk_mul_f32 v[4:5], v[4:5], v[78:79] op_sel_hi:[1,0]
	v_pk_mul_f32 v[2:3], v[2:3], v[78:79] op_sel_hi:[1,0]
	s_mov_b64 s[0:1], 0
	v_pk_mul_f32 v[28:29], v[32:33], v[28:29]
	v_pk_mul_f32 v[26:27], v[30:31], v[26:27]
	v_bfe_u32 v32, v28, 16, 1
	v_bfe_u32 v30, v26, 16, 1
	v_bfe_u32 v31, v27, 16, 1
	v_bfe_u32 v33, v29, 16, 1
	v_add3_u32 v26, v26, v30, s5
	v_add3_u32 v28, v28, v32, s5
	v_add3_u32 v27, v27, v31, s5
	v_add3_u32 v29, v29, v33, s5
	v_lshrrev_b32_e32 v26, 16, v26
	v_lshrrev_b32_e32 v28, 16, v28
	v_and_or_b32 v26, v27, s7, v26
	v_and_or_b32 v27, v29, s7, v28
	global_store_dwordx2 v[62:63], v[26:27], off offset:512
	s_nop 1
	v_mov_b32_e32 v26, v136
	v_mov_b32_e32 v27, v137
	v_mov_b32_e32 v28, v138
	v_mov_b32_e32 v29, v139
	v_pk_mul_f32 v[24:25], v[28:29], v[24:25]
	v_pk_mul_f32 v[22:23], v[26:27], v[22:23]
	v_bfe_u32 v28, v24, 16, 1
	v_bfe_u32 v26, v22, 16, 1
	v_bfe_u32 v27, v23, 16, 1
	v_bfe_u32 v29, v25, 16, 1
	v_add3_u32 v22, v22, v26, s5
	v_add3_u32 v24, v24, v28, s5
	v_add3_u32 v23, v23, v27, s5
	v_add3_u32 v25, v25, v29, s5
	v_lshrrev_b32_e32 v22, 16, v22
	v_lshrrev_b32_e32 v24, 16, v24
	v_and_or_b32 v22, v23, s7, v22
	v_and_or_b32 v23, v25, s7, v24
	global_store_dwordx2 v[62:63], v[22:23], off offset:1024
	s_nop 1
	v_mov_b32_e32 v22, v140
	v_mov_b32_e32 v23, v141
	v_mov_b32_e32 v24, v142
	v_mov_b32_e32 v25, v143
	v_pk_mul_f32 v[20:21], v[24:25], v[20:21]
	v_pk_mul_f32 v[18:19], v[22:23], v[18:19]
	v_bfe_u32 v24, v20, 16, 1
	v_bfe_u32 v22, v18, 16, 1
	v_bfe_u32 v23, v19, 16, 1
	v_bfe_u32 v25, v21, 16, 1
	v_add3_u32 v18, v18, v22, s5
	v_add3_u32 v20, v20, v24, s5
	v_add3_u32 v19, v19, v23, s5
	v_add3_u32 v21, v21, v25, s5
	v_lshrrev_b32_e32 v18, 16, v18
	v_lshrrev_b32_e32 v20, 16, v20
	v_and_or_b32 v18, v19, s7, v18
	v_and_or_b32 v19, v21, s7, v20
	global_store_dwordx2 v[62:63], v[18:19], off offset:1536
	s_nop 1
	v_mov_b32_e32 v18, v144
	v_mov_b32_e32 v19, v145
	v_mov_b32_e32 v20, v146
	v_mov_b32_e32 v21, v147
	v_pk_mul_f32 v[16:17], v[20:21], v[16:17]
	v_pk_mul_f32 v[14:15], v[18:19], v[14:15]
	v_bfe_u32 v20, v16, 16, 1
	v_bfe_u32 v18, v14, 16, 1
	v_bfe_u32 v19, v15, 16, 1
	v_bfe_u32 v21, v17, 16, 1
	v_add3_u32 v14, v14, v18, s5
	v_add3_u32 v16, v16, v20, s5
	v_add3_u32 v15, v15, v19, s5
	v_add3_u32 v17, v17, v21, s5
	v_lshrrev_b32_e32 v14, 16, v14
	v_lshrrev_b32_e32 v16, 16, v16
	v_and_or_b32 v14, v15, s7, v14
	v_and_or_b32 v15, v17, s7, v16
	global_store_dwordx2 v[62:63], v[14:15], off offset:2048
	s_nop 1
	v_mov_b32_e32 v14, v148
	v_mov_b32_e32 v15, v149
	v_mov_b32_e32 v16, v150
	v_mov_b32_e32 v17, v151
	v_pk_mul_f32 v[12:13], v[12:13], v[16:17]
	v_pk_mul_f32 v[10:11], v[10:11], v[14:15]
	v_bfe_u32 v16, v12, 16, 1
	v_bfe_u32 v14, v10, 16, 1
	v_bfe_u32 v15, v11, 16, 1
	v_bfe_u32 v17, v13, 16, 1
	v_add3_u32 v10, v10, v14, s5
	v_add3_u32 v12, v12, v16, s5
	v_add3_u32 v11, v11, v15, s5
	v_add3_u32 v13, v13, v17, s5
	v_lshrrev_b32_e32 v10, 16, v10
	v_lshrrev_b32_e32 v12, 16, v12
	v_and_or_b32 v10, v11, s7, v10
	v_and_or_b32 v11, v13, s7, v12
	global_store_dwordx2 v[62:63], v[10:11], off offset:2560
	s_nop 1
	v_mov_b32_e32 v10, v152
	v_mov_b32_e32 v11, v153
	v_mov_b32_e32 v12, v154
	v_mov_b32_e32 v13, v155
	v_pk_mul_f32 v[8:9], v[8:9], v[12:13]
	v_pk_mul_f32 v[6:7], v[6:7], v[10:11]
	v_bfe_u32 v12, v8, 16, 1
	v_bfe_u32 v10, v6, 16, 1
	v_bfe_u32 v11, v7, 16, 1
	v_bfe_u32 v13, v9, 16, 1
	v_add3_u32 v6, v6, v10, s5
	v_add3_u32 v8, v8, v12, s5
	v_add3_u32 v7, v7, v11, s5
	v_add3_u32 v9, v9, v13, s5
	v_lshrrev_b32_e32 v6, 16, v6
	v_lshrrev_b32_e32 v8, 16, v8
	v_and_or_b32 v6, v7, s7, v6
	v_and_or_b32 v7, v9, s7, v8
	global_store_dwordx2 v[62:63], v[6:7], off offset:3072
	s_nop 1
	v_mov_b32_e32 v6, v156
	v_mov_b32_e32 v7, v157
	v_mov_b32_e32 v8, v158
	v_mov_b32_e32 v9, v159
	v_pk_mul_f32 v[2:3], v[2:3], v[6:7]
	v_pk_mul_f32 v[4:5], v[4:5], v[8:9]
.LBB0_341:
	s_andn2_b64 vcc, exec, s[0:1]
	s_cbranch_vccnz .LBB0_338
	global_load_dwordx4 v[30:33], v[58:59], off offset:-4096
	global_load_dwordx4 v[26:29], v[58:59], off offset:-3072
	global_load_dwordx4 v[22:25], v[58:59], off offset:-2048
	global_load_dwordx4 v[14:17], v[58:59], off
	global_load_dwordx4 v[18:21], v[58:59], off offset:-1024
	global_load_dwordx4 v[10:13], v[58:59], off offset:1024
	global_load_dwordx4 v[2:5], v[58:59], off offset:3072
	global_load_dwordx4 v[6:9], v[58:59], off offset:2048
	global_load_dwordx4 v[74:77], v[48:49], off
	global_load_dwordx4 v[132:135], v[48:49], off offset:1024
	global_load_dwordx4 v[136:139], v[48:49], off offset:2048
	global_load_dwordx4 v[140:143], v[48:49], off offset:3072
	global_load_dwordx4 v[144:147], v[50:51], off
	global_load_dwordx4 v[148:151], v[52:53], off
	global_load_dwordx4 v[152:155], v[54:55], off
	global_load_dwordx4 v[156:159], v[56:57], off
	v_cmp_lt_i32_e32 vcc, v67, v66
	s_waitcnt vmcnt(0)
	v_mov_b32_e32 v78, v31
	v_cndmask_b32_e32 v62, v65, v67, vcc
	v_mov_b32_e32 v79, v27
	v_mov_b32_e32 v84, v33
	v_mov_b32_e32 v85, v29
	v_lshlrev_b32_e32 v73, 2, v62
	v_mov_b32_e32 v62, v30
	v_mov_b32_e32 v63, v26
	v_mov_b32_e32 v80, v32
	v_mov_b32_e32 v81, v28
	v_pk_mul_f32 v[86:87], v[24:25], v[24:25]
	v_pk_mul_f32 v[88:89], v[22:23], v[22:23]
	v_pk_mul_f32 v[78:79], v[78:79], v[78:79]
	v_pk_mul_f32 v[84:85], v[84:85], v[84:85]
	v_pk_mov_b32 v[100:101], v[88:89], v[86:87] op_sel:[1,0]
	v_mov_b32_e32 v89, v87
	v_pk_fma_f32 v[62:63], v[62:63], v[62:63], v[78:79]
	v_pk_fma_f32 v[78:79], v[80:81], v[80:81], v[84:85]
	v_mul_f32_e32 v82, v19, v19
	v_mul_f32_e32 v90, v21, v21
	v_pk_add_f32 v[80:81], v[100:101], v[88:89]
	v_pk_add_f32 v[62:63], v[62:63], v[78:79]
	v_mul_f32_e32 v99, v14, v14
	v_mul_f32_e32 v104, v15, v15
	v_mul_f32_e32 v105, v16, v16
	v_mul_f32_e32 v106, v17, v17
	v_pk_fma_f32 v[86:87], v[18:19], v[18:19], v[82:83] op_sel_hi:[1,1,0]
	v_pk_fma_f32 v[90:91], v[20:21], v[20:21], v[90:91] op_sel_hi:[1,1,0]
	v_pk_add_f32 v[78:79], v[80:81], v[80:81] op_sel:[0,1] op_sel_hi:[1,0]
	v_pk_add_f32 v[62:63], v[62:63], v[62:63] op_sel:[0,1] op_sel_hi:[1,0]
	v_pk_mul_f32 v[92:93], v[12:13], v[12:13]
	v_pk_mul_f32 v[94:95], v[10:11], v[10:11]
	v_mov_b32_e32 v87, v105
	v_mov_b32_e32 v91, v106
	v_mov_b32_e32 v79, v104
	v_mov_b32_e32 v63, v99
	v_pk_mov_b32 v[102:103], v[94:95], v[92:93] op_sel:[1,0]
	v_mov_b32_e32 v95, v93
	v_pk_add_f32 v[80:81], v[86:87], v[90:91]
	v_pk_add_f32 v[62:63], v[62:63], v[78:79]
	v_mul_f32_e32 v96, v7, v7
	v_mul_f32_e32 v98, v9, v9
	v_pk_add_f32 v[84:85], v[102:103], v[94:95]
	v_pk_add_f32 v[62:63], v[62:63], v[80:81]
	v_mul_f32_e32 v107, v2, v2
	v_mul_f32_e32 v108, v3, v3
	v_mul_f32_e32 v109, v4, v4
	v_mul_f32_e32 v110, v5, v5
	v_pk_fma_f32 v[92:93], v[6:7], v[6:7], v[96:97] op_sel_hi:[1,1,0]
	v_pk_fma_f32 v[96:97], v[8:9], v[8:9], v[98:99] op_sel_hi:[1,1,0]
	v_pk_add_f32 v[84:85], v[84:85], v[84:85] op_sel:[0,1] op_sel_hi:[1,0]
	v_pk_add_f32 v[62:63], v[62:63], v[62:63] op_sel:[0,1] op_sel_hi:[1,0]
	v_mov_b32_e32 v93, v109
	v_mov_b32_e32 v97, v110
	v_mov_b32_e32 v85, v108
	v_mov_b32_e32 v63, v107
	v_pk_add_f32 v[86:87], v[92:93], v[96:97]
	v_pk_add_f32 v[62:63], v[62:63], v[84:85]
	v_cmp_lt_i32_e32 vcc, v68, v66
	v_pk_add_f32 v[62:63], v[62:63], v[86:87]
	s_nop 0
	v_add_f32_e32 v62, v62, v63
	ds_bpermute_b32 v63, v73, v62
	v_cndmask_b32_e32 v73, v65, v68, vcc
	v_lshlrev_b32_e32 v73, 2, v73
	v_cmp_lt_i32_e32 vcc, v69, v66
	s_waitcnt lgkmcnt(0)
	v_add_f32_e32 v62, v62, v63
	ds_bpermute_b32 v63, v73, v62
	v_cndmask_b32_e32 v73, v65, v69, vcc
	v_lshlrev_b32_e32 v73, 2, v73
	v_cmp_lt_i32_e32 vcc, v70, v66
	s_waitcnt lgkmcnt(0)
	v_add_f32_e32 v62, v62, v63
	ds_bpermute_b32 v63, v73, v62
	v_cndmask_b32_e32 v73, v65, v70, vcc
	v_lshlrev_b32_e32 v73, 2, v73
	v_cmp_lt_i32_e32 vcc, v71, v66
	s_waitcnt lgkmcnt(0)
	v_add_f32_e32 v62, v62, v63
	ds_bpermute_b32 v63, v73, v62
	v_cndmask_b32_e32 v73, v65, v71, vcc
	v_lshlrev_b32_e32 v73, 2, v73
	v_cmp_lt_i32_e32 vcc, v72, v66
	s_waitcnt lgkmcnt(0)
	v_add_f32_e32 v62, v62, v63
	ds_bpermute_b32 v63, v73, v62
	v_cndmask_b32_e32 v73, v65, v72, vcc
	v_lshlrev_b32_e32 v73, 2, v73
	s_waitcnt lgkmcnt(0)
	v_add_f32_e32 v62, v62, v63
	ds_bpermute_b32 v63, v73, v62
	s_waitcnt lgkmcnt(0)
	v_add_f32_e32 v62, v62, v63
	v_fmamk_f32 v62, v62, 0x3a000000, v1
	v_mul_f32_e32 v63, 0x4f800000, v62
	v_cmp_gt_f32_e32 vcc, s3, v62
	s_nop 1
	v_cndmask_b32_e32 v62, v62, v63, vcc
	v_sqrt_f32_e32 v63, v62
	s_nop 0
	v_add_u32_e32 v73, -1, v63
	v_add_u32_e32 v78, 1, v63
	v_fma_f32 v79, -v73, v63, v62
	v_fma_f32 v80, -v78, v63, v62
	v_cmp_ge_f32_e64 s[0:1], 0, v79
	s_nop 1
	v_cndmask_b32_e64 v63, v63, v73, s[0:1]
	v_cmp_lt_f32_e64 s[0:1], 0, v80
	s_nop 1
	v_cndmask_b32_e64 v63, v63, v78, s[0:1]
	v_mul_f32_e32 v73, 0x37800000, v63
	v_cndmask_b32_e32 v63, v63, v73, vcc
	v_cmp_class_f32_e32 vcc, v62, v64
	s_nop 1
	v_cndmask_b32_e32 v62, v63, v62, vcc
	v_div_scale_f32 v63, s[0:1], v62, v62, 1.0
	v_rcp_f32_e32 v73, v63
	v_div_scale_f32 v78, vcc, 1.0, v62, 1.0
	v_fma_f32 v79, -v63, v73, 1.0
	v_fmac_f32_e32 v73, v79, v73
	v_mul_f32_e32 v79, v78, v73
	v_fma_f32 v80, -v63, v79, v78
	v_fmac_f32_e32 v79, v80, v73
	v_fma_f32 v63, -v63, v79, v78
	v_div_fmas_f32 v63, v63, v73, v79
	v_div_fixup_f32 v62, v63, v62, 1.0
	v_pk_mul_f32 v[30:31], v[30:31], v[62:63] op_sel_hi:[1,0]
	v_pk_mul_f32 v[32:33], v[32:33], v[62:63] op_sel_hi:[1,0]
	v_pk_mul_f32 v[30:31], v[74:75], v[30:31]
	v_pk_mul_f32 v[32:33], v[76:77], v[32:33]
	v_bfe_u32 v63, v30, 16, 1
	v_bfe_u32 v74, v32, 16, 1
	v_bfe_u32 v73, v31, 16, 1
	v_bfe_u32 v75, v33, 16, 1
	v_add3_u32 v30, v30, v63, s5
	v_add3_u32 v32, v32, v74, s5
	v_add3_u32 v31, v31, v73, s5
	v_add3_u32 v33, v33, v75, s5
	v_lshrrev_b32_e32 v30, 16, v30
	v_lshrrev_b32_e32 v32, 16, v32
	v_and_or_b32 v30, v31, s7, v30
	v_and_or_b32 v31, v33, s7, v32
	global_store_dwordx2 v[60:61], v[30:31], off
	s_nop 1
	v_mov_b32_e32 v30, v132
	v_mov_b32_e32 v31, v133
	v_mov_b32_e32 v32, v134
	v_mov_b32_e32 v33, v135
	v_pk_mul_f32 v[26:27], v[26:27], v[62:63] op_sel_hi:[1,0]
	v_pk_mul_f32 v[28:29], v[28:29], v[62:63] op_sel_hi:[1,0]
	v_pk_mul_f32 v[22:23], v[22:23], v[62:63] op_sel_hi:[1,0]
	v_pk_mul_f32 v[24:25], v[24:25], v[62:63] op_sel_hi:[1,0]
	v_pk_mul_f32 v[18:19], v[18:19], v[62:63] op_sel_hi:[1,0]
	v_pk_mul_f32 v[20:21], v[20:21], v[62:63] op_sel_hi:[1,0]
	v_pk_mul_f32 v[14:15], v[14:15], v[62:63] op_sel_hi:[1,0]
	v_pk_mul_f32 v[16:17], v[16:17], v[62:63] op_sel_hi:[1,0]
	v_pk_mul_f32 v[10:11], v[10:11], v[62:63] op_sel_hi:[1,0]
	v_pk_mul_f32 v[12:13], v[12:13], v[62:63] op_sel_hi:[1,0]
	v_pk_mul_f32 v[6:7], v[6:7], v[62:63] op_sel_hi:[1,0]
	v_pk_mul_f32 v[8:9], v[8:9], v[62:63] op_sel_hi:[1,0]
	v_pk_mul_f32 v[4:5], v[4:5], v[62:63] op_sel_hi:[1,0]
	v_pk_mul_f32 v[2:3], v[2:3], v[62:63] op_sel_hi:[1,0]
	v_mov_b64_e32 v[62:63], v[60:61]
	v_pk_mul_f32 v[28:29], v[32:33], v[28:29]
	v_pk_mul_f32 v[26:27], v[30:31], v[26:27]
	v_bfe_u32 v32, v28, 16, 1
	v_bfe_u32 v30, v26, 16, 1
	v_bfe_u32 v31, v27, 16, 1
	v_bfe_u32 v33, v29, 16, 1
	v_add3_u32 v26, v26, v30, s5
	v_add3_u32 v28, v28, v32, s5
	v_add3_u32 v27, v27, v31, s5
	v_add3_u32 v29, v29, v33, s5
	v_lshrrev_b32_e32 v26, 16, v26
	v_lshrrev_b32_e32 v28, 16, v28
	v_and_or_b32 v26, v27, s7, v26
	v_and_or_b32 v27, v29, s7, v28
	global_store_dwordx2 v[60:61], v[26:27], off offset:512
	s_nop 1
	v_mov_b32_e32 v26, v136
	v_mov_b32_e32 v27, v137
	v_mov_b32_e32 v28, v138
	v_mov_b32_e32 v29, v139
	v_pk_mul_f32 v[24:25], v[28:29], v[24:25]
	v_pk_mul_f32 v[22:23], v[26:27], v[22:23]
	v_bfe_u32 v28, v24, 16, 1
	v_bfe_u32 v26, v22, 16, 1
	v_bfe_u32 v27, v23, 16, 1
	v_bfe_u32 v29, v25, 16, 1
	v_add3_u32 v22, v22, v26, s5
	v_add3_u32 v24, v24, v28, s5
	v_add3_u32 v23, v23, v27, s5
	v_add3_u32 v25, v25, v29, s5
	v_lshrrev_b32_e32 v22, 16, v22
	v_lshrrev_b32_e32 v24, 16, v24
	v_and_or_b32 v22, v23, s7, v22
	v_and_or_b32 v23, v25, s7, v24
	global_store_dwordx2 v[60:61], v[22:23], off offset:1024
	s_nop 1
	v_mov_b32_e32 v22, v140
	v_mov_b32_e32 v23, v141
	v_mov_b32_e32 v24, v142
	v_mov_b32_e32 v25, v143
	v_pk_mul_f32 v[20:21], v[24:25], v[20:21]
	v_pk_mul_f32 v[18:19], v[22:23], v[18:19]
	v_bfe_u32 v24, v20, 16, 1
	v_bfe_u32 v22, v18, 16, 1
	v_bfe_u32 v23, v19, 16, 1
	v_bfe_u32 v25, v21, 16, 1
	v_add3_u32 v18, v18, v22, s5
	v_add3_u32 v20, v20, v24, s5
	v_add3_u32 v19, v19, v23, s5
	v_add3_u32 v21, v21, v25, s5
	v_lshrrev_b32_e32 v18, 16, v18
	v_lshrrev_b32_e32 v20, 16, v20
	v_and_or_b32 v18, v19, s7, v18
	v_and_or_b32 v19, v21, s7, v20
	global_store_dwordx2 v[60:61], v[18:19], off offset:1536
	s_nop 1
	v_mov_b32_e32 v18, v144
	v_mov_b32_e32 v19, v145
	v_mov_b32_e32 v20, v146
	v_mov_b32_e32 v21, v147
	v_pk_mul_f32 v[16:17], v[20:21], v[16:17]
	v_pk_mul_f32 v[14:15], v[18:19], v[14:15]
	v_bfe_u32 v20, v16, 16, 1
	v_bfe_u32 v18, v14, 16, 1
	v_bfe_u32 v19, v15, 16, 1
	v_bfe_u32 v21, v17, 16, 1
	v_add3_u32 v14, v14, v18, s5
	v_add3_u32 v16, v16, v20, s5
	v_add3_u32 v15, v15, v19, s5
	v_add3_u32 v17, v17, v21, s5
	v_lshrrev_b32_e32 v14, 16, v14
	v_lshrrev_b32_e32 v16, 16, v16
	v_and_or_b32 v14, v15, s7, v14
	v_and_or_b32 v15, v17, s7, v16
	global_store_dwordx2 v[60:61], v[14:15], off offset:2048
	s_nop 1
	v_mov_b32_e32 v14, v148
	v_mov_b32_e32 v15, v149
	v_mov_b32_e32 v16, v150
	v_mov_b32_e32 v17, v151
	v_pk_mul_f32 v[12:13], v[12:13], v[16:17]
	v_pk_mul_f32 v[10:11], v[10:11], v[14:15]
	v_bfe_u32 v16, v12, 16, 1
	v_bfe_u32 v14, v10, 16, 1
	v_bfe_u32 v15, v11, 16, 1
	v_bfe_u32 v17, v13, 16, 1
	v_add3_u32 v10, v10, v14, s5
	v_add3_u32 v12, v12, v16, s5
	v_add3_u32 v11, v11, v15, s5
	v_add3_u32 v13, v13, v17, s5
	v_lshrrev_b32_e32 v10, 16, v10
	v_lshrrev_b32_e32 v12, 16, v12
	v_and_or_b32 v10, v11, s7, v10
	v_and_or_b32 v11, v13, s7, v12
	global_store_dwordx2 v[60:61], v[10:11], off offset:2560
	s_nop 1
	v_mov_b32_e32 v10, v152
	v_mov_b32_e32 v11, v153
	v_mov_b32_e32 v12, v154
	v_mov_b32_e32 v13, v155
	v_pk_mul_f32 v[8:9], v[8:9], v[12:13]
	v_pk_mul_f32 v[6:7], v[6:7], v[10:11]
	v_bfe_u32 v12, v8, 16, 1
	v_bfe_u32 v10, v6, 16, 1
	v_bfe_u32 v11, v7, 16, 1
	v_bfe_u32 v13, v9, 16, 1
	v_add3_u32 v6, v6, v10, s5
	v_add3_u32 v8, v8, v12, s5
	v_add3_u32 v7, v7, v11, s5
	v_add3_u32 v9, v9, v13, s5
	v_lshrrev_b32_e32 v6, 16, v6
	v_lshrrev_b32_e32 v8, 16, v8
	v_and_or_b32 v6, v7, s7, v6
	v_and_or_b32 v7, v9, s7, v8
	global_store_dwordx2 v[60:61], v[6:7], off offset:3072
	s_nop 1
	v_mov_b32_e32 v6, v156
	v_mov_b32_e32 v7, v157
	v_mov_b32_e32 v8, v158
	v_mov_b32_e32 v9, v159
	v_pk_mul_f32 v[2:3], v[2:3], v[6:7]
	v_pk_mul_f32 v[4:5], v[4:5], v[8:9]
	s_branch .LBB0_338
